# sliding-window attention (2 sites): V base + first four transposed V reads issued in the hazard padding before the row-max reduction, size neutral; on top of v165
# speedup vs baseline: 1.0034x; 1.0034x over previous
.LBB0_638:
	v_add_u32_e32 v198, s23, v144
	ds_read_b64_tr_b16 v[182:183], v198 offset:36864
	ds_read_b64_tr_b16 v[184:185], v198 offset:37376
	ds_read_b64_tr_b16 v[186:187], v198 offset:37888
	ds_read_b64_tr_b16 v[188:189], v198 offset:38400
	s_nop 5
	v_max3_f32 v0, v83, v67, v84
	v_max3_f32 v0, v0, v68, v82
	v_max3_f32 v0, v0, v66, v85
	v_max3_f32 v0, v0, v69, v86
	v_max3_f32 v0, v0, v70, v87
	v_max3_f32 v0, v0, v71, v88
	v_max3_f32 v0, v0, v72, v89
	v_max3_f32 v0, v0, v73, v90
	v_max3_f32 v0, v0, v74, v91
	v_max3_f32 v0, v0, v75, v92
	v_max3_f32 v0, v0, v76, v93
	v_max3_f32 v0, v0, v77, v94
	v_max3_f32 v0, v0, v78, v95
	v_max3_f32 v0, v0, v79, v96
	v_max3_f32 v0, v0, v80, v97
	v_max_f32_e64 v0, v0, v81
	v_cmp_lt_f32_e32 vcc, s85, v0
	s_cbranch_vccz .LBB0_640
	ds_bpermute_b32 v3, v143, v0
	s_waitcnt lgkmcnt(0)
	v_max3_f32 v0, v0, v3, 0
	v_exp_f32_e64 v4, -v0
	v_add_f32_e32 v145, v145, v0
	v_xor_b32_e32 v50, 0x80000000, v145
	v_pk_add_f32 v[82:83], v[82:83], v[0:1] op_sel_hi:[1,0] neg_lo:[0,1] neg_hi:[0,1]
	v_pk_add_f32 v[66:67], v[66:67], v[0:1] op_sel_hi:[1,0] neg_lo:[0,1] neg_hi:[0,1]
	v_pk_add_f32 v[84:85], v[84:85], v[0:1] op_sel_hi:[1,0] neg_lo:[0,1] neg_hi:[0,1]
	v_pk_add_f32 v[68:69], v[68:69], v[0:1] op_sel_hi:[1,0] neg_lo:[0,1] neg_hi:[0,1]
	v_pk_add_f32 v[86:87], v[86:87], v[0:1] op_sel_hi:[1,0] neg_lo:[0,1] neg_hi:[0,1]
	v_pk_add_f32 v[70:71], v[70:71], v[0:1] op_sel_hi:[1,0] neg_lo:[0,1] neg_hi:[0,1]
	v_pk_add_f32 v[88:89], v[88:89], v[0:1] op_sel_hi:[1,0] neg_lo:[0,1] neg_hi:[0,1]
	v_pk_add_f32 v[72:73], v[72:73], v[0:1] op_sel_hi:[1,0] neg_lo:[0,1] neg_hi:[0,1]
	v_pk_add_f32 v[90:91], v[90:91], v[0:1] op_sel_hi:[1,0] neg_lo:[0,1] neg_hi:[0,1]
	v_pk_add_f32 v[74:75], v[74:75], v[0:1] op_sel_hi:[1,0] neg_lo:[0,1] neg_hi:[0,1]
	v_pk_add_f32 v[92:93], v[92:93], v[0:1] op_sel_hi:[1,0] neg_lo:[0,1] neg_hi:[0,1]
	v_pk_add_f32 v[76:77], v[76:77], v[0:1] op_sel_hi:[1,0] neg_lo:[0,1] neg_hi:[0,1]
	v_pk_add_f32 v[94:95], v[94:95], v[0:1] op_sel_hi:[1,0] neg_lo:[0,1] neg_hi:[0,1]
	v_pk_add_f32 v[78:79], v[78:79], v[0:1] op_sel_hi:[1,0] neg_lo:[0,1] neg_hi:[0,1]
	v_pk_add_f32 v[96:97], v[96:97], v[0:1] op_sel_hi:[1,0] neg_lo:[0,1] neg_hi:[0,1]
	v_pk_add_f32 v[80:81], v[80:81], v[0:1] op_sel_hi:[1,0] neg_lo:[0,1] neg_hi:[0,1]
	v_pk_mul_f32 v[48:49], v[48:49], v[4:5] op_sel_hi:[1,0]
	v_pk_mul_f32 v[46:47], v[46:47], v[4:5] op_sel_hi:[1,0]
	v_pk_mul_f32 v[44:45], v[44:45], v[4:5] op_sel_hi:[1,0]
	v_pk_mul_f32 v[42:43], v[42:43], v[4:5] op_sel_hi:[1,0]
	v_pk_mul_f32 v[40:41], v[40:41], v[4:5] op_sel_hi:[1,0]
	v_pk_mul_f32 v[38:39], v[38:39], v[4:5] op_sel_hi:[1,0]
	v_pk_mul_f32 v[36:37], v[36:37], v[4:5] op_sel_hi:[1,0]
	v_pk_mul_f32 v[34:35], v[34:35], v[4:5] op_sel_hi:[1,0]
	v_pk_mul_f32 v[32:33], v[32:33], v[4:5] op_sel_hi:[1,0]
	v_pk_mul_f32 v[30:31], v[30:31], v[4:5] op_sel_hi:[1,0]
	v_pk_mul_f32 v[28:29], v[28:29], v[4:5] op_sel_hi:[1,0]
	v_pk_mul_f32 v[26:27], v[26:27], v[4:5] op_sel_hi:[1,0]
	v_pk_mul_f32 v[24:25], v[24:25], v[4:5] op_sel_hi:[1,0]
	v_pk_mul_f32 v[22:23], v[22:23], v[4:5] op_sel_hi:[1,0]
	v_pk_mul_f32 v[20:21], v[20:21], v[4:5] op_sel_hi:[1,0]
	v_pk_mul_f32 v[18:19], v[18:19], v[4:5] op_sel_hi:[1,0]
	v_mov_b32_e32 v51, v50
	v_mov_b32_e32 v52, v50
	v_mov_b32_e32 v53, v50
	v_mov_b32_e32 v54, v50
	v_mov_b32_e32 v55, v50
	v_mov_b32_e32 v56, v50
	v_mov_b32_e32 v57, v50
	v_mov_b32_e32 v58, v50
	v_mov_b32_e32 v59, v50
	v_mov_b32_e32 v60, v50
	v_mov_b32_e32 v61, v50
	v_mov_b32_e32 v62, v50
	v_mov_b32_e32 v63, v50
	v_mov_b32_e32 v64, v50
	v_mov_b32_e32 v65, v50
	v_mul_f32_e32 v148, v148, v4
.LBB0_640:
	v_exp_f32_e32 v3, v82
	v_exp_f32_e32 v150, v66
	v_exp_f32_e32 v0, v83
	v_exp_f32_e32 v8, v67
	v_exp_f32_e32 v151, v68
	v_add_f32_e32 v9, v150, v3
	v_exp_f32_e32 v10, v69
	v_pk_add_f32 v[4:5], v[8:9], v[0:1]
	v_exp_f32_e32 v9, v84
	v_pk_add_f32 v[6:7], v[4:5], v[4:5] op_sel_hi:[0,1]
	v_exp_f32_e32 v6, v85
	v_exp_f32_e32 v14, v71
	v_add_f32_e32 v11, v151, v9
	v_exp_f32_e32 v68, v73
	v_pk_add_f32 v[4:5], v[10:11], v[6:7]
	v_exp_f32_e32 v7, v86
	v_pk_add_f32 v[12:13], v[4:5], v[4:5] op_sel_hi:[0,1]
	v_exp_f32_e32 v11, v70
	v_exp_f32_e32 v12, v87
	v_exp_f32_e32 v87, v80
	v_exp_f32_e32 v86, v81
	v_add_f32_e32 v15, v11, v7
	v_pk_add_f32 v[4:5], v[14:15], v[12:13]
	v_exp_f32_e32 v13, v88
	v_pk_add_f32 v[66:67], v[4:5], v[4:5] op_sel_hi:[0,1]
	v_exp_f32_e32 v15, v72
	v_exp_f32_e32 v66, v89
	v_exp_f32_e32 v72, v75
	v_add_f32_e32 v69, v15, v13
	v_pk_add_f32 v[4:5], v[68:69], v[66:67]
	v_exp_f32_e32 v67, v90
	v_pk_add_f32 v[70:71], v[4:5], v[4:5] op_sel_hi:[0,1]
	v_exp_f32_e32 v69, v74
	v_exp_f32_e32 v70, v91
	v_add_f32_e32 v73, v69, v67
	v_pk_add_f32 v[4:5], v[72:73], v[70:71]
	v_exp_f32_e32 v71, v92
	v_pk_add_f32 v[74:75], v[4:5], v[4:5] op_sel_hi:[0,1]
	v_exp_f32_e32 v73, v76
	v_exp_f32_e32 v74, v93
	v_exp_f32_e32 v76, v77
	v_add_f32_e32 v77, v73, v71
	v_pk_add_f32 v[4:5], v[76:77], v[74:75]
	s_nop 0
	v_pk_add_f32 v[82:83], v[4:5], v[4:5] op_sel_hi:[0,1]
	v_exp_f32_e32 v75, v94
	v_exp_f32_e32 v77, v78
	v_exp_f32_e32 v82, v95
	v_exp_f32_e32 v78, v79
	v_add_f32_e32 v79, v77, v75
	v_pk_add_f32 v[4:5], v[78:79], v[82:83]
	s_nop 0
	v_pk_add_f32 v[84:85], v[4:5], v[4:5] op_sel_hi:[0,1]
	v_cvt_pk_bf16_f32 v4, v3, v0
	v_exp_f32_e32 v83, v96
	v_exp_f32_e32 v84, v97
	v_cvt_pk_bf16_f32 v5, v9, v6
	v_cvt_pk_bf16_f32 v6, v7, v12
	v_cvt_pk_bf16_f32 v7, v13, v66
	v_cvt_pk_bf16_f32 v8, v150, v8
	v_cvt_pk_bf16_f32 v9, v151, v10
	v_cvt_pk_bf16_f32 v10, v11, v14
	v_cvt_pk_bf16_f32 v11, v15, v68
	v_cvt_pk_bf16_f32 v12, v67, v70
	v_cvt_pk_bf16_f32 v13, v71, v74
	v_cvt_pk_bf16_f32 v14, v75, v82
	v_cvt_pk_bf16_f32 v15, v83, v84
	v_cvt_pk_bf16_f32 v66, v69, v72
	v_cvt_pk_bf16_f32 v67, v73, v76
	v_cvt_pk_bf16_f32 v68, v77, v78
	v_cvt_pk_bf16_f32 v69, v87, v86
	s_waitcnt lgkmcnt(2)
	v_mfma_f32_32x32x16_bf16 v[34:49], v[182:185], v[4:7], v[34:49]
	ds_read_b64_tr_b16 v[70:71], v198 offset:40960
	ds_read_b64_tr_b16 v[72:73], v198 offset:41472
	ds_read_b64_tr_b16 v[78:79], v198 offset:41984
	ds_read_b64_tr_b16 v[80:81], v198 offset:42496
	v_add_f32_e32 v87, v87, v83
	s_waitcnt lgkmcnt(2)
	v_mfma_f32_32x32x16_bf16 v[18:33], v[70:73], v[4:7], v[18:33]
	v_mfma_f32_32x32x16_bf16 v[34:49], v[186:189], v[12:15], v[34:49]
	s_waitcnt lgkmcnt(0)
	v_mfma_f32_32x32x16_bf16 v[18:33], v[78:81], v[12:15], v[18:33]
	ds_read_b64_tr_b16 v[4:5], v198 offset:38912
	ds_read_b64_tr_b16 v[6:7], v198 offset:39424
	ds_read_b64_tr_b16 v[12:13], v198 offset:39936
	ds_read_b64_tr_b16 v[14:15], v198 offset:40448
	s_waitcnt lgkmcnt(2)
	v_mfma_f32_32x32x16_bf16 v[34:49], v[4:7], v[8:11], v[34:49]
	ds_read_b64_tr_b16 v[4:5], v198 offset:43008
	ds_read_b64_tr_b16 v[6:7], v198 offset:43520
	ds_read_b64_tr_b16 v[70:71], v198 offset:44032
	ds_read_b64_tr_b16 v[72:73], v198 offset:44544
	s_waitcnt lgkmcnt(2)
	v_mfma_f32_32x32x16_bf16 v[18:33], v[4:7], v[8:11], v[18:33]
	v_add_f32_e64 v4, v86, v84
	v_add_f32_e64 v5, v87, v85
	v_add_f32_e32 v0, v4, v5
	v_add_f32_e32 v148, v148, v0
	v_mfma_f32_32x32x16_bf16 v[34:49], v[12:15], v[66:69], v[34:49]
	s_waitcnt lgkmcnt(0)
	v_mfma_f32_32x32x16_bf16 v[18:33], v[70:73], v[66:69], v[18:33]

.LBB0_644:
	v_add_u32_e32 v198, s23, v144
	ds_read_b64_tr_b16 v[182:183], v198 offset:45056
	ds_read_b64_tr_b16 v[184:185], v198 offset:45568
	ds_read_b64_tr_b16 v[186:187], v198 offset:46080
	ds_read_b64_tr_b16 v[188:189], v198 offset:46592
	s_nop 5
	v_max3_f32 v0, v83, v67, v84
	v_max3_f32 v0, v0, v68, v82
	v_max3_f32 v0, v0, v66, v85
	v_max3_f32 v0, v0, v69, v86
	v_max3_f32 v0, v0, v70, v87
	v_max3_f32 v0, v0, v71, v88
	v_max3_f32 v0, v0, v72, v89
	v_max3_f32 v0, v0, v73, v90
	v_max3_f32 v0, v0, v74, v91
	v_max3_f32 v0, v0, v75, v92
	v_max3_f32 v0, v0, v76, v93
	v_max3_f32 v0, v0, v77, v94
	v_max3_f32 v0, v0, v78, v95
	v_max3_f32 v0, v0, v79, v96
	v_max3_f32 v0, v0, v80, v97
	v_max_f32_e32 v0, v0, v81
	v_cmp_lt_f32_e32 vcc, s85, v0
	s_cbranch_vccz .LBB0_646
	ds_bpermute_b32 v2, v143, v0
	s_waitcnt lgkmcnt(0)
	v_max3_f32 v0, v0, v2, 0
	v_exp_f32_e64 v2, -v0
	v_add_f32_e32 v145, v145, v0
	v_xor_b32_e32 v50, 0x80000000, v145
	v_pk_add_f32 v[82:83], v[82:83], v[0:1] op_sel_hi:[1,0] neg_lo:[0,1] neg_hi:[0,1]
	v_pk_add_f32 v[66:67], v[66:67], v[0:1] op_sel_hi:[1,0] neg_lo:[0,1] neg_hi:[0,1]
	v_pk_add_f32 v[84:85], v[84:85], v[0:1] op_sel_hi:[1,0] neg_lo:[0,1] neg_hi:[0,1]
	v_pk_add_f32 v[68:69], v[68:69], v[0:1] op_sel_hi:[1,0] neg_lo:[0,1] neg_hi:[0,1]
	v_pk_add_f32 v[86:87], v[86:87], v[0:1] op_sel_hi:[1,0] neg_lo:[0,1] neg_hi:[0,1]
	v_pk_add_f32 v[70:71], v[70:71], v[0:1] op_sel_hi:[1,0] neg_lo:[0,1] neg_hi:[0,1]
	v_pk_add_f32 v[88:89], v[88:89], v[0:1] op_sel_hi:[1,0] neg_lo:[0,1] neg_hi:[0,1]
	v_pk_add_f32 v[72:73], v[72:73], v[0:1] op_sel_hi:[1,0] neg_lo:[0,1] neg_hi:[0,1]
	v_pk_add_f32 v[90:91], v[90:91], v[0:1] op_sel_hi:[1,0] neg_lo:[0,1] neg_hi:[0,1]
	v_pk_add_f32 v[74:75], v[74:75], v[0:1] op_sel_hi:[1,0] neg_lo:[0,1] neg_hi:[0,1]
	v_pk_add_f32 v[92:93], v[92:93], v[0:1] op_sel_hi:[1,0] neg_lo:[0,1] neg_hi:[0,1]
	v_pk_add_f32 v[76:77], v[76:77], v[0:1] op_sel_hi:[1,0] neg_lo:[0,1] neg_hi:[0,1]
	v_pk_add_f32 v[94:95], v[94:95], v[0:1] op_sel_hi:[1,0] neg_lo:[0,1] neg_hi:[0,1]
	v_pk_add_f32 v[78:79], v[78:79], v[0:1] op_sel_hi:[1,0] neg_lo:[0,1] neg_hi:[0,1]
	v_pk_add_f32 v[96:97], v[96:97], v[0:1] op_sel_hi:[1,0] neg_lo:[0,1] neg_hi:[0,1]
	v_pk_add_f32 v[80:81], v[80:81], v[0:1] op_sel_hi:[1,0] neg_lo:[0,1] neg_hi:[0,1]
	v_pk_mul_f32 v[48:49], v[48:49], v[2:3] op_sel_hi:[1,0]
	v_pk_mul_f32 v[46:47], v[46:47], v[2:3] op_sel_hi:[1,0]
	v_pk_mul_f32 v[44:45], v[44:45], v[2:3] op_sel_hi:[1,0]
	v_pk_mul_f32 v[42:43], v[42:43], v[2:3] op_sel_hi:[1,0]
	v_pk_mul_f32 v[40:41], v[40:41], v[2:3] op_sel_hi:[1,0]
	v_pk_mul_f32 v[38:39], v[38:39], v[2:3] op_sel_hi:[1,0]
	v_pk_mul_f32 v[36:37], v[36:37], v[2:3] op_sel_hi:[1,0]
	v_pk_mul_f32 v[34:35], v[34:35], v[2:3] op_sel_hi:[1,0]
	v_pk_mul_f32 v[32:33], v[32:33], v[2:3] op_sel_hi:[1,0]
	v_pk_mul_f32 v[30:31], v[30:31], v[2:3] op_sel_hi:[1,0]
	v_pk_mul_f32 v[28:29], v[28:29], v[2:3] op_sel_hi:[1,0]
	v_pk_mul_f32 v[26:27], v[26:27], v[2:3] op_sel_hi:[1,0]
	v_pk_mul_f32 v[24:25], v[24:25], v[2:3] op_sel_hi:[1,0]
	v_pk_mul_f32 v[22:23], v[22:23], v[2:3] op_sel_hi:[1,0]
	v_pk_mul_f32 v[20:21], v[20:21], v[2:3] op_sel_hi:[1,0]
	v_pk_mul_f32 v[18:19], v[18:19], v[2:3] op_sel_hi:[1,0]
	v_mov_b32_e32 v51, v50
	v_mov_b32_e32 v52, v50
	v_mov_b32_e32 v53, v50
	v_mov_b32_e32 v54, v50
	v_mov_b32_e32 v55, v50
	v_mov_b32_e32 v56, v50
	v_mov_b32_e32 v57, v50
	v_mov_b32_e32 v58, v50
	v_mov_b32_e32 v59, v50
	v_mov_b32_e32 v60, v50
	v_mov_b32_e32 v61, v50
	v_mov_b32_e32 v62, v50
	v_mov_b32_e32 v63, v50
	v_mov_b32_e32 v64, v50
	v_mov_b32_e32 v65, v50
	v_mul_f32_e32 v148, v148, v2
.LBB0_646:
	v_exp_f32_e32 v150, v82
	v_exp_f32_e32 v151, v66
	v_exp_f32_e32 v0, v83
	v_exp_f32_e32 v6, v67
	v_exp_f32_e32 v152, v68
	v_add_f32_e32 v7, v151, v150
	v_exp_f32_e32 v8, v69
	v_pk_add_f32 v[2:3], v[6:7], v[0:1]
	v_exp_f32_e32 v7, v84
	v_pk_add_f32 v[4:5], v[2:3], v[2:3] op_sel_hi:[0,1]
	v_exp_f32_e32 v4, v85
	v_exp_f32_e32 v12, v71
	v_add_f32_e32 v9, v152, v7
	v_exp_f32_e32 v66, v73
	v_pk_add_f32 v[2:3], v[8:9], v[4:5]
	v_exp_f32_e32 v5, v86
	v_pk_add_f32 v[10:11], v[2:3], v[2:3] op_sel_hi:[0,1]
	v_exp_f32_e32 v9, v70
	v_exp_f32_e32 v10, v87
	v_exp_f32_e32 v70, v75
	v_exp_f32_e32 v85, v96
	v_add_f32_e32 v13, v9, v5
	v_pk_add_f32 v[2:3], v[12:13], v[10:11]
	v_exp_f32_e32 v11, v88
	v_pk_add_f32 v[14:15], v[2:3], v[2:3] op_sel_hi:[0,1]
	v_exp_f32_e32 v13, v72
	v_exp_f32_e32 v14, v89
	v_exp_f32_e32 v86, v80
	v_exp_f32_e32 v84, v81
	v_add_f32_e32 v67, v13, v11
	v_pk_add_f32 v[2:3], v[66:67], v[14:15]
	v_exp_f32_e32 v15, v90
	v_pk_add_f32 v[68:69], v[2:3], v[2:3] op_sel_hi:[0,1]
	v_exp_f32_e32 v67, v74
	v_exp_f32_e32 v68, v91
	v_exp_f32_e32 v74, v77
	v_add_f32_e32 v71, v67, v15
	v_pk_add_f32 v[2:3], v[70:71], v[68:69]
	v_exp_f32_e32 v69, v92
	v_pk_add_f32 v[72:73], v[2:3], v[2:3] op_sel_hi:[0,1]
	v_exp_f32_e32 v71, v76
	v_exp_f32_e32 v72, v93
	v_add_f32_e32 v75, v71, v69
	v_pk_add_f32 v[2:3], v[74:75], v[72:73]
	v_exp_f32_e32 v73, v94
	v_pk_add_f32 v[76:77], v[2:3], v[2:3] op_sel_hi:[0,1]
	v_exp_f32_e32 v75, v78
	v_exp_f32_e32 v76, v95
	v_exp_f32_e32 v78, v79
	v_add_f32_e32 v79, v75, v73
	v_pk_add_f32 v[2:3], v[78:79], v[76:77]
	s_nop 0
	v_pk_add_f32 v[82:83], v[2:3], v[2:3] op_sel_hi:[0,1]
	v_cvt_pk_bf16_f32 v2, v150, v0
	v_exp_f32_e32 v82, v97
	v_cvt_pk_bf16_f32 v3, v7, v4
	v_cvt_pk_bf16_f32 v4, v5, v10
	v_cvt_pk_bf16_f32 v5, v11, v14
	v_cvt_pk_bf16_f32 v6, v151, v6
	v_cvt_pk_bf16_f32 v7, v152, v8
	v_cvt_pk_bf16_f32 v8, v9, v12
	v_cvt_pk_bf16_f32 v9, v13, v66
	v_cvt_pk_bf16_f32 v10, v15, v68
	v_cvt_pk_bf16_f32 v11, v69, v72
	v_cvt_pk_bf16_f32 v12, v73, v76
	v_cvt_pk_bf16_f32 v13, v85, v82
	v_cvt_pk_bf16_f32 v66, v67, v70
	v_cvt_pk_bf16_f32 v67, v71, v74
	v_cvt_pk_bf16_f32 v68, v75, v78
	v_cvt_pk_bf16_f32 v69, v86, v84
	s_waitcnt lgkmcnt(2)
	v_mfma_f32_32x32x16_bf16 v[34:49], v[182:185], v[2:5], v[34:49]
	ds_read_b64_tr_b16 v[70:71], v198 offset:49152
	ds_read_b64_tr_b16 v[72:73], v198 offset:49664
	ds_read_b64_tr_b16 v[78:79], v198 offset:50176
	ds_read_b64_tr_b16 v[80:81], v198 offset:50688
	v_add_f32_e32 v85, v86, v85
	s_waitcnt lgkmcnt(2)
	v_mfma_f32_32x32x16_bf16 v[18:33], v[70:73], v[2:5], v[18:33]
	v_mfma_f32_32x32x16_bf16 v[34:49], v[186:189], v[10:13], v[34:49]
	s_waitcnt lgkmcnt(0)
	v_mfma_f32_32x32x16_bf16 v[18:33], v[78:81], v[10:13], v[18:33]
	ds_read_b64_tr_b16 v[2:3], v198 offset:47104
	ds_read_b64_tr_b16 v[4:5], v198 offset:47616
	ds_read_b64_tr_b16 v[10:11], v198 offset:48128
	ds_read_b64_tr_b16 v[12:13], v198 offset:48640
	s_waitcnt lgkmcnt(2)
	v_mfma_f32_32x32x16_bf16 v[34:49], v[2:5], v[6:9], v[34:49]
	ds_read_b64_tr_b16 v[2:3], v198 offset:51200
	ds_read_b64_tr_b16 v[4:5], v198 offset:51712
	ds_read_b64_tr_b16 v[70:71], v198 offset:52224
	ds_read_b64_tr_b16 v[72:73], v198 offset:52736
	s_waitcnt lgkmcnt(2)
	v_mfma_f32_32x32x16_bf16 v[18:33], v[2:5], v[6:9], v[18:33]
	v_add_f32_e64 v2, v84, v82
	v_add_f32_e64 v3, v85, v83
	v_add_f32_e32 v0, v2, v3
	v_add_f32_e32 v148, v148, v0
	v_mfma_f32_32x32x16_bf16 v[34:49], v[10:13], v[66:69], v[34:49]
	s_waitcnt lgkmcnt(0)
	v_mfma_f32_32x32x16_bf16 v[18:33], v[70:73], v[66:69], v[18:33]
